# grid barrier tight polling: no s_sleep between polls of the top counter
# baseline (speedup 1.0000x reference)
.Lxb_spin:
	global_load_dword v5, v145, s[4:5] sc1
	s_add_i32 s36, s36, 1
	s_waitcnt vmcnt(0)
	v_cmp_lt_u32_e32 vcc, v5, v4
	s_cbranch_vccz .Lxb_done
	s_cmp_lt_u32 s36, 0x40000
	s_cbranch_scc1 .Lxb_spin
